# P0 adaLN: silu(c) fill loads all in flight + L2 warm-up of the wave's w_ada slice (on top of v2)
# speedup vs baseline: 1.0059x; 1.0059x over previous
; #define LAS __attribute__((address_space(3)))
; __device__ __forceinline__ float siluf_(float x) { return x * __builtin_amdgcn_rcpf(1.0f + __builtin_amdgcn_exp2f(x * -1.4426950408889634f)); }
; __device__ __forceinline__ void phase0(const Args& a, LAS unsigned char* lds, int G) {
;     ...
;     if ((int)blockIdx.x < NMOD / 64) {
;         LAS float* scT = (LAS float*)lds;
;         LAS float* red = (LAS float*)(lds + 65536);
;         for (int idx = tid; idx < 16 * 1024; idx += 512) { const int b = idx >> 10, k = idx & 1023; scT[k * 16 + b] = siluf_(c_in[idx]); }
;     ...
;         const float* wp = w_ada + (size_t)(wid * 128) * NMOD + n0 + lane;
; #pragma unroll 8
;         for (int k = 0; k < 128; ++k) { const float wv = wp[(size_t)k * NMOD]; const LAS f32x4* s4 = (const LAS f32x4*)(scT + (wid * 128 + k) * 16);
.LBB0_23:
	s_or_b64 exec, exec, s[4:5]
	s_ashr_i32 s3, s2, 6
	s_cmpk_gt_i32 s92, 0x5f
	s_cbranch_scc1 .LBB0_33
	s_movk_i32 s2, 0x4000
	v_cmp_gt_i32_e32 vcc, s2, v0
	s_and_saveexec_b64 s[4:5], vcc
	s_cbranch_execz .LBB0_27
	v_readlane_b32 s8, v236, 10
	v_readlane_b32 s10, v236, 12
	v_readlane_b32 s11, v236, 13
	v_readlane_b32 s9, v236, 11
	s_waitcnt lgkmcnt(1)
	v_mov_b32_e32 v6, s10
	s_waitcnt lgkmcnt(0)
	v_mov_b32_e32 v7, s11
	v_ashrrev_i32_e32 v1, 31, v0
	v_lshlrev_b32_e32 v3, 4, v0
	v_lshl_add_u64 v[6:7], v[0:1], 2, v[6:7]
	s_mov_b64 s[6:7], 0
	s_mov_b64 s[8:9], 0x800
	s_movk_i32 s2, 0x3dff
	v_mov_b32_e32 v1, v0
	v_readlane_b32 s12, v236, 14
	v_readlane_b32 s13, v236, 15
	v_readlane_b32 s14, v236, 16
	v_readlane_b32 s15, v236, 17
	v_readlane_b32 s16, v236, 18
	v_readlane_b32 s17, v236, 19
	v_readlane_b32 s18, v236, 20
	v_readlane_b32 s19, v236, 21
	v_readlane_b32 s20, v236, 22
	v_readlane_b32 s21, v236, 23
	v_readlane_b32 s22, v236, 24
	v_readlane_b32 s23, v236, 25
	s_mov_b64 s[8:9], 0x1000
	global_load_dword v176, v[6:7], off
	global_load_dword v177, v[6:7], off offset:2048
	v_lshl_add_u64 v[6:7], v[6:7], 0, s[8:9]
	global_load_dword v178, v[6:7], off
	global_load_dword v179, v[6:7], off offset:2048
	v_lshl_add_u64 v[6:7], v[6:7], 0, s[8:9]
	global_load_dword v180, v[6:7], off
	global_load_dword v181, v[6:7], off offset:2048
	v_lshl_add_u64 v[6:7], v[6:7], 0, s[8:9]
	global_load_dword v182, v[6:7], off
	global_load_dword v183, v[6:7], off offset:2048
	v_lshl_add_u64 v[6:7], v[6:7], 0, s[8:9]
	global_load_dword v184, v[6:7], off
	global_load_dword v185, v[6:7], off offset:2048
	v_lshl_add_u64 v[6:7], v[6:7], 0, s[8:9]
	global_load_dword v186, v[6:7], off
	global_load_dword v187, v[6:7], off offset:2048
	v_lshl_add_u64 v[6:7], v[6:7], 0, s[8:9]
	global_load_dword v188, v[6:7], off
	global_load_dword v189, v[6:7], off offset:2048
	v_lshl_add_u64 v[6:7], v[6:7], 0, s[8:9]
	global_load_dword v190, v[6:7], off
	global_load_dword v191, v[6:7], off offset:2048
	v_lshl_add_u64 v[6:7], v[6:7], 0, s[8:9]
	global_load_dword v192, v[6:7], off
	global_load_dword v193, v[6:7], off offset:2048
	v_lshl_add_u64 v[6:7], v[6:7], 0, s[8:9]
	global_load_dword v194, v[6:7], off
	global_load_dword v195, v[6:7], off offset:2048
	v_lshl_add_u64 v[6:7], v[6:7], 0, s[8:9]
	global_load_dword v196, v[6:7], off
	global_load_dword v197, v[6:7], off offset:2048
	v_lshl_add_u64 v[6:7], v[6:7], 0, s[8:9]
	global_load_dword v198, v[6:7], off
	global_load_dword v199, v[6:7], off offset:2048
	v_lshl_add_u64 v[6:7], v[6:7], 0, s[8:9]
	global_load_dword v200, v[6:7], off
	global_load_dword v201, v[6:7], off offset:2048
	v_lshl_add_u64 v[6:7], v[6:7], 0, s[8:9]
	global_load_dword v202, v[6:7], off
	global_load_dword v203, v[6:7], off offset:2048
	v_lshl_add_u64 v[6:7], v[6:7], 0, s[8:9]
	global_load_dword v204, v[6:7], off
	global_load_dword v205, v[6:7], off offset:2048
	v_lshl_add_u64 v[6:7], v[6:7], 0, s[8:9]
	global_load_dword v206, v[6:7], off
	global_load_dword v207, v[6:7], off offset:2048
	s_mul_i32 s16, s3, 0x300000
	s_lshl_b32 s17, s92, 8
	s_add_u32 s16, s16, s17
	s_add_u32 s16, s12, s16
	s_addc_u32 s17, s13, 0
	v_lshrrev_b32_e32 v212, 3, v4
	v_and_b32_e32 v213, 4, v4
	v_mul_u32_u24_e32 v212, 0x6000, v212
	v_lshl_add_u32 v212, v213, 5, v212
	global_load_dword v208, v212, s[16:17]
	v_add_u32_e32 v212, 0xc0000, v212
	global_load_dword v209, v212, s[16:17]
	v_add_u32_e32 v212, 0xc0000, v212
	global_load_dword v210, v212, s[16:17]
	v_add_u32_e32 v212, 0xc0000, v212
	global_load_dword v211, v212, s[16:17]
	v_lshlrev_b32_e32 v8, 6, v0
	s_waitcnt vmcnt(34)
	v_mul_f32_e32 v9, 0xbfb8aa3b, v176
	v_mul_f32_e32 v10, 0xbfb8aa3b, v177
	v_exp_f32_e32 v9, v9
	v_exp_f32_e32 v10, v10
	v_add_f32_e32 v9, 1.0, v9
	v_add_f32_e32 v10, 1.0, v10
	v_rcp_f32_e32 v9, v9
	v_rcp_f32_e32 v10, v10
	v_mul_f32_e32 v9, v176, v9
	v_mul_f32_e32 v10, v177, v10
	ds_write_b32 v8, v9
	ds_write_b32 v8, v10 offset:32768
	s_waitcnt vmcnt(32)
	v_mul_f32_e32 v9, 0xbfb8aa3b, v178
	v_mul_f32_e32 v10, 0xbfb8aa3b, v179
	v_exp_f32_e32 v9, v9
	v_exp_f32_e32 v10, v10
	v_add_f32_e32 v9, 1.0, v9
	v_add_f32_e32 v10, 1.0, v10
	v_rcp_f32_e32 v9, v9
	v_rcp_f32_e32 v10, v10
	v_mul_f32_e32 v9, v178, v9
	v_mul_f32_e32 v10, v179, v10
	ds_write_b32 v8, v9 offset:4
	ds_write_b32 v8, v10 offset:32772
	s_waitcnt vmcnt(30)
	v_mul_f32_e32 v9, 0xbfb8aa3b, v180
	v_mul_f32_e32 v10, 0xbfb8aa3b, v181
	v_exp_f32_e32 v9, v9
	v_exp_f32_e32 v10, v10
	v_add_f32_e32 v9, 1.0, v9
	v_add_f32_e32 v10, 1.0, v10
	v_rcp_f32_e32 v9, v9
	v_rcp_f32_e32 v10, v10
	v_mul_f32_e32 v9, v180, v9
	v_mul_f32_e32 v10, v181, v10
	ds_write_b32 v8, v9 offset:8
	ds_write_b32 v8, v10 offset:32776
	s_waitcnt vmcnt(28)
; __device__ __forceinline__ float siluf_(float x) { return x * __builtin_amdgcn_rcpf(1.0f + __builtin_amdgcn_exp2f(x * -1.4426950408889634f)); }
; __device__ __forceinline__ void phase0(const Args& a, LAS unsigned char* lds, int G) {
;     ...
;         for (int idx = tid; idx < 16 * 1024; idx += 512) { const int b = idx >> 10, k = idx & 1023; scT[k * 16 + b] = siluf_(c_in[idx]); }
	v_mul_f32_e32 v9, 0xbfb8aa3b, v182
	v_mul_f32_e32 v10, 0xbfb8aa3b, v183
	v_exp_f32_e32 v9, v9
	v_exp_f32_e32 v10, v10
	v_add_f32_e32 v9, 1.0, v9
	v_add_f32_e32 v10, 1.0, v10
	v_rcp_f32_e32 v9, v9
	v_rcp_f32_e32 v10, v10
	v_mul_f32_e32 v9, v182, v9
	v_mul_f32_e32 v10, v183, v10
	ds_write_b32 v8, v9 offset:12
	ds_write_b32 v8, v10 offset:32780
	s_waitcnt vmcnt(26)
	v_mul_f32_e32 v9, 0xbfb8aa3b, v184
	v_mul_f32_e32 v10, 0xbfb8aa3b, v185
	v_exp_f32_e32 v9, v9
	v_exp_f32_e32 v10, v10
	v_add_f32_e32 v9, 1.0, v9
	v_add_f32_e32 v10, 1.0, v10
	v_rcp_f32_e32 v9, v9
	v_rcp_f32_e32 v10, v10
	v_mul_f32_e32 v9, v184, v9
	v_mul_f32_e32 v10, v185, v10
	ds_write_b32 v8, v9 offset:16
	ds_write_b32 v8, v10 offset:32784
	s_waitcnt vmcnt(24)
	v_mul_f32_e32 v9, 0xbfb8aa3b, v186
	v_mul_f32_e32 v10, 0xbfb8aa3b, v187
	v_exp_f32_e32 v9, v9
	v_exp_f32_e32 v10, v10
	v_add_f32_e32 v9, 1.0, v9
	v_add_f32_e32 v10, 1.0, v10
	v_rcp_f32_e32 v9, v9
	v_rcp_f32_e32 v10, v10
	v_mul_f32_e32 v9, v186, v9
	v_mul_f32_e32 v10, v187, v10
	ds_write_b32 v8, v9 offset:20
	ds_write_b32 v8, v10 offset:32788
	s_waitcnt vmcnt(22)
	v_mul_f32_e32 v9, 0xbfb8aa3b, v188
	v_mul_f32_e32 v10, 0xbfb8aa3b, v189
	v_exp_f32_e32 v9, v9
	v_exp_f32_e32 v10, v10
	v_add_f32_e32 v9, 1.0, v9
	v_add_f32_e32 v10, 1.0, v10
	v_rcp_f32_e32 v9, v9
	v_rcp_f32_e32 v10, v10
	v_mul_f32_e32 v9, v188, v9
	v_mul_f32_e32 v10, v189, v10
	ds_write_b32 v8, v9 offset:24
	ds_write_b32 v8, v10 offset:32792
	s_waitcnt vmcnt(20)
	v_mul_f32_e32 v9, 0xbfb8aa3b, v190
	v_mul_f32_e32 v10, 0xbfb8aa3b, v191
	v_exp_f32_e32 v9, v9
	v_exp_f32_e32 v10, v10
	v_add_f32_e32 v9, 1.0, v9
	v_add_f32_e32 v10, 1.0, v10
	v_rcp_f32_e32 v9, v9
	v_rcp_f32_e32 v10, v10
	v_mul_f32_e32 v9, v190, v9
	v_mul_f32_e32 v10, v191, v10
	ds_write_b32 v8, v9 offset:28
	ds_write_b32 v8, v10 offset:32796
	s_waitcnt vmcnt(18)
	v_mul_f32_e32 v9, 0xbfb8aa3b, v192
	v_mul_f32_e32 v10, 0xbfb8aa3b, v193
	v_exp_f32_e32 v9, v9
	v_exp_f32_e32 v10, v10
	v_add_f32_e32 v9, 1.0, v9
	v_add_f32_e32 v10, 1.0, v10
	v_rcp_f32_e32 v9, v9
	v_rcp_f32_e32 v10, v10
	v_mul_f32_e32 v9, v192, v9
	v_mul_f32_e32 v10, v193, v10
	ds_write_b32 v8, v9 offset:32
	ds_write_b32 v8, v10 offset:32800
	s_waitcnt vmcnt(16)
	v_mul_f32_e32 v9, 0xbfb8aa3b, v194
	v_mul_f32_e32 v10, 0xbfb8aa3b, v195
	v_exp_f32_e32 v9, v9
	v_exp_f32_e32 v10, v10
	v_add_f32_e32 v9, 1.0, v9
	v_add_f32_e32 v10, 1.0, v10
	v_rcp_f32_e32 v9, v9
	v_rcp_f32_e32 v10, v10
	v_mul_f32_e32 v9, v194, v9
	v_mul_f32_e32 v10, v195, v10
	ds_write_b32 v8, v9 offset:36
	ds_write_b32 v8, v10 offset:32804
	s_waitcnt vmcnt(14)
	v_mul_f32_e32 v9, 0xbfb8aa3b, v196
	v_mul_f32_e32 v10, 0xbfb8aa3b, v197
	v_exp_f32_e32 v9, v9
	v_exp_f32_e32 v10, v10
	v_add_f32_e32 v9, 1.0, v9
	v_add_f32_e32 v10, 1.0, v10
	v_rcp_f32_e32 v9, v9
	v_rcp_f32_e32 v10, v10
	v_mul_f32_e32 v9, v196, v9
	v_mul_f32_e32 v10, v197, v10
	ds_write_b32 v8, v9 offset:40
	ds_write_b32 v8, v10 offset:32808
	s_waitcnt vmcnt(12)
	v_mul_f32_e32 v9, 0xbfb8aa3b, v198
	v_mul_f32_e32 v10, 0xbfb8aa3b, v199
	v_exp_f32_e32 v9, v9
	v_exp_f32_e32 v10, v10
	v_add_f32_e32 v9, 1.0, v9
	v_add_f32_e32 v10, 1.0, v10
	v_rcp_f32_e32 v9, v9
	v_rcp_f32_e32 v10, v10
	v_mul_f32_e32 v9, v198, v9
	v_mul_f32_e32 v10, v199, v10
	ds_write_b32 v8, v9 offset:44
	ds_write_b32 v8, v10 offset:32812
	s_waitcnt vmcnt(10)
	v_mul_f32_e32 v9, 0xbfb8aa3b, v200
	v_mul_f32_e32 v10, 0xbfb8aa3b, v201
	v_exp_f32_e32 v9, v9
	v_exp_f32_e32 v10, v10
	v_add_f32_e32 v9, 1.0, v9
	v_add_f32_e32 v10, 1.0, v10
	v_rcp_f32_e32 v9, v9
	v_rcp_f32_e32 v10, v10
	v_mul_f32_e32 v9, v200, v9
	v_mul_f32_e32 v10, v201, v10
	ds_write_b32 v8, v9 offset:48
	ds_write_b32 v8, v10 offset:32816
	s_waitcnt vmcnt(8)
	v_mul_f32_e32 v9, 0xbfb8aa3b, v202
	v_mul_f32_e32 v10, 0xbfb8aa3b, v203
	v_exp_f32_e32 v9, v9
	v_exp_f32_e32 v10, v10
	v_add_f32_e32 v9, 1.0, v9
	v_add_f32_e32 v10, 1.0, v10
	v_rcp_f32_e32 v9, v9
	v_rcp_f32_e32 v10, v10
	v_mul_f32_e32 v9, v202, v9
	v_mul_f32_e32 v10, v203, v10
	ds_write_b32 v8, v9 offset:52
	ds_write_b32 v8, v10 offset:32820
	s_waitcnt vmcnt(6)
	v_mul_f32_e32 v9, 0xbfb8aa3b, v204
	v_mul_f32_e32 v10, 0xbfb8aa3b, v205
	v_exp_f32_e32 v9, v9
	v_exp_f32_e32 v10, v10
	v_add_f32_e32 v9, 1.0, v9
	v_add_f32_e32 v10, 1.0, v10
	v_rcp_f32_e32 v9, v9
	v_rcp_f32_e32 v10, v10
	v_mul_f32_e32 v9, v204, v9
	v_mul_f32_e32 v10, v205, v10
	ds_write_b32 v8, v9 offset:56
	ds_write_b32 v8, v10 offset:32824
	s_waitcnt vmcnt(4)
	v_mul_f32_e32 v9, 0xbfb8aa3b, v206
	v_mul_f32_e32 v10, 0xbfb8aa3b, v207
	v_exp_f32_e32 v9, v9
	v_exp_f32_e32 v10, v10
	v_add_f32_e32 v9, 1.0, v9
	v_add_f32_e32 v10, 1.0, v10
	v_rcp_f32_e32 v9, v9
	v_rcp_f32_e32 v10, v10
	v_mul_f32_e32 v9, v206, v9
	v_mul_f32_e32 v10, v207, v10
	ds_write_b32 v8, v9 offset:60
	ds_write_b32 v8, v10 offset:32828
